# hand-scheduled SwiGLU epilogue (in-place, 8 independent chains, no nops) on top of deferred conversion
# speedup vs baseline: 1.0374x; 1.0029x over previous
; #define PG8_LAS __attribute__((address_space(3)))
; __device__ __forceinline__ unsigned cvt_pk_bf16(float lo, float hi) { unsigned r; asm volatile("v_cvt_pk_bf16_f32 %0, %1, %2" : "=v"(r) : "v"(lo), "v"(hi)); return r; }
;     __device__ __forceinline__ void operator()(const f32x4 (&acc)[2][2][4][2], const Unit& u, int wr, int wc, int fr, int fq, const PG8_LAS float* tab) const {
;         const int row0 = u.pm * BM + wr * 64 + fr, col0 = u.pn * HALF + wc * 32 + 8 * fq;
; #pragma unroll
;         for (int ai = 0; ai < 2; ++ai)
; #pragma unroll
;             for (int m = 0; m < 4; ++m) { const int row = row0 + ai * HALF + m * 16;
;                 const float rs = tab[ai * HALF + wr * 64 + m * 16 + fr];
;                 float hv[8];
; #pragma unroll
;                 for (int n = 0; n < 2; ++n)
; #pragma unroll
;                     for (int j = 0; j < 4; ++j) { const float g = acc[ai][0][m][n][j] * rs, up = acc[ai][1][m][n][j] * rs;
;                         const float e = __builtin_amdgcn_exp2f(g * -1.4426950408889634f);
;                         hv[4 * n + j] = g * up * __builtin_amdgcn_rcpf(1.0f + e); }
;                 u32x4 w; w.x = cvt_pk_bf16(hv[0], hv[1]); w.y = cvt_pk_bf16(hv[2], hv[3]); w.z = cvt_pk_bf16(hv[4], hv[5]); w.w = cvt_pk_bf16(hv[6], hv[7]);
;                 *(u32x4*)(H + (size_t)row * ldh + col0) = w; }
;     }
.LBB0_223:
	v_lshl_add_u32 v148, s59, 10, v144
	ds_read_b32 v150, v148
	v_lshl_add_u32 v140, s29, 7, v145
	v_lshl_add_u32 v147, s28, 8, v142
	s_andn2_b64 vcc, exec, s[0:1]
	v_ashrrev_i32_e32 v141, 31, v140
	s_waitcnt lgkmcnt(0)
	v_mul_f32_e32 v126, v150, v126
	v_mul_f32_e32 v127, v150, v127
	v_mul_f32_e32 v128, v150, v128
	v_mul_f32_e32 v129, v150, v129
	v_mul_f32_e32 v118, v150, v118
	v_mul_f32_e32 v119, v150, v119
	v_mul_f32_e32 v120, v150, v120
	v_mul_f32_e32 v121, v150, v121
	v_mul_f32_e32 v122, v150, v122
	v_mul_f32_e32 v123, v150, v123
	v_mul_f32_e32 v124, v150, v124
	v_mul_f32_e32 v125, v150, v125
	v_mul_f32_e32 v114, v150, v114
	v_mul_f32_e32 v115, v150, v115
	v_mul_f32_e32 v116, v150, v116
	v_mul_f32_e32 v117, v150, v117
	ds_read_b32 v152, v148 offset:64
	v_mul_f32_e32 v122, v126, v122
	v_mul_f32_e32 v123, v127, v123
	v_mul_f32_e32 v124, v128, v124
	v_mul_f32_e32 v125, v129, v125
	v_mul_f32_e32 v114, v118, v114
	v_mul_f32_e32 v115, v119, v115
	v_mul_f32_e32 v116, v120, v116
	v_mul_f32_e32 v117, v121, v117
	v_mul_f32_e32 v126, 0xbfb8aa3b, v126
	v_mul_f32_e32 v127, 0xbfb8aa3b, v127
	v_mul_f32_e32 v128, 0xbfb8aa3b, v128
	v_mul_f32_e32 v129, 0xbfb8aa3b, v129
	v_mul_f32_e32 v118, 0xbfb8aa3b, v118
	v_mul_f32_e32 v119, 0xbfb8aa3b, v119
	v_mul_f32_e32 v120, 0xbfb8aa3b, v120
	v_mul_f32_e32 v121, 0xbfb8aa3b, v121
	v_exp_f32_e32 v126, v126
	v_exp_f32_e32 v127, v127
	v_exp_f32_e32 v128, v128
	v_exp_f32_e32 v129, v129
	v_exp_f32_e32 v118, v118
	v_exp_f32_e32 v119, v119
	v_exp_f32_e32 v120, v120
	v_exp_f32_e32 v121, v121
	v_add_f32_e32 v126, 1.0, v126
	v_add_f32_e32 v127, 1.0, v127
	v_add_f32_e32 v128, 1.0, v128
	v_add_f32_e32 v129, 1.0, v129
	v_add_f32_e32 v118, 1.0, v118
	v_add_f32_e32 v119, 1.0, v119
	v_add_f32_e32 v120, 1.0, v120
	v_add_f32_e32 v121, 1.0, v121
	v_rcp_f32_e32 v126, v126
	v_rcp_f32_e32 v127, v127
	v_rcp_f32_e32 v128, v128
	v_rcp_f32_e32 v129, v129
	v_rcp_f32_e32 v118, v118
	v_rcp_f32_e32 v119, v119
	v_rcp_f32_e32 v120, v120
	v_rcp_f32_e32 v121, v121
	v_mul_f32_e32 v122, v122, v126
	v_mul_f32_e32 v123, v123, v127
	v_mul_f32_e32 v124, v124, v128
	v_mul_f32_e32 v125, v125, v129
	v_mul_f32_e32 v114, v114, v118
	v_mul_f32_e32 v115, v115, v119
	v_mul_f32_e32 v116, v116, v120
	v_mul_f32_e32 v117, v117, v121
	v_cvt_pk_bf16_f32 v126, v122, v123
	v_cvt_pk_bf16_f32 v127, v124, v125
	v_cvt_pk_bf16_f32 v128, v114, v115
	v_cvt_pk_bf16_f32 v129, v116, v117
	v_lshlrev_b64 v[116:117], 1, v[140:141]
	v_mov_b64_e32 v[114:115], s[16:17]
	v_mad_i64_i32 v[120:121], s[28:29], v147, s63, v[114:115]
	v_lshl_add_u64 v[120:121], v[120:121], 0, v[116:117]
	global_store_dwordx4 v[120:121], v[126:129], off
	s_waitcnt lgkmcnt(0)
	v_mul_f32_e32 v110, v152, v110
	v_mul_f32_e32 v111, v152, v111
	v_mul_f32_e32 v112, v152, v112
	v_mul_f32_e32 v113, v152, v113
	v_mul_f32_e32 v102, v152, v102
	v_mul_f32_e32 v103, v152, v103
	v_mul_f32_e32 v104, v152, v104
	v_mul_f32_e32 v105, v152, v105
	v_mul_f32_e32 v106, v152, v106
	v_mul_f32_e32 v107, v152, v107
	v_mul_f32_e32 v108, v152, v108
	v_mul_f32_e32 v109, v152, v109
	v_mul_f32_e32 v98, v152, v98
	v_mul_f32_e32 v99, v152, v99
	v_mul_f32_e32 v100, v152, v100
	v_mul_f32_e32 v101, v152, v101
	ds_read_b32 v150, v148 offset:128
	v_mul_f32_e32 v106, v110, v106
	v_mul_f32_e32 v107, v111, v107
	v_mul_f32_e32 v108, v112, v108
	v_mul_f32_e32 v109, v113, v109
	v_mul_f32_e32 v98, v102, v98
	v_mul_f32_e32 v99, v103, v99
	v_mul_f32_e32 v100, v104, v100
	v_mul_f32_e32 v101, v105, v101
	v_mul_f32_e32 v110, 0xbfb8aa3b, v110
	v_mul_f32_e32 v111, 0xbfb8aa3b, v111
	v_mul_f32_e32 v112, 0xbfb8aa3b, v112
	v_mul_f32_e32 v113, 0xbfb8aa3b, v113
	v_mul_f32_e32 v102, 0xbfb8aa3b, v102
	v_mul_f32_e32 v103, 0xbfb8aa3b, v103
	v_mul_f32_e32 v104, 0xbfb8aa3b, v104
	v_mul_f32_e32 v105, 0xbfb8aa3b, v105
	v_exp_f32_e32 v110, v110
	v_exp_f32_e32 v111, v111
	v_exp_f32_e32 v112, v112
	v_exp_f32_e32 v113, v113
	v_exp_f32_e32 v102, v102
	v_exp_f32_e32 v103, v103
	v_exp_f32_e32 v104, v104
	v_exp_f32_e32 v105, v105
	v_add_f32_e32 v110, 1.0, v110
	v_add_f32_e32 v111, 1.0, v111
	v_add_f32_e32 v112, 1.0, v112
	v_add_f32_e32 v113, 1.0, v113
	v_add_f32_e32 v102, 1.0, v102
	v_add_f32_e32 v103, 1.0, v103
	v_add_f32_e32 v104, 1.0, v104
	v_add_f32_e32 v105, 1.0, v105
	v_rcp_f32_e32 v110, v110
	v_rcp_f32_e32 v111, v111
	v_rcp_f32_e32 v112, v112
	v_rcp_f32_e32 v113, v113
	v_rcp_f32_e32 v102, v102
	v_rcp_f32_e32 v103, v103
	v_rcp_f32_e32 v104, v104
	v_rcp_f32_e32 v105, v105
	v_mul_f32_e32 v106, v106, v110
	v_mul_f32_e32 v107, v107, v111
	v_mul_f32_e32 v108, v108, v112
	v_mul_f32_e32 v109, v109, v113
	v_mul_f32_e32 v98, v98, v102
	v_mul_f32_e32 v99, v99, v103
	v_mul_f32_e32 v100, v100, v104
	v_mul_f32_e32 v101, v101, v105
	v_cvt_pk_bf16_f32 v110, v106, v107
	v_cvt_pk_bf16_f32 v111, v108, v109
	v_cvt_pk_bf16_f32 v112, v98, v99
	v_cvt_pk_bf16_f32 v113, v100, v101
	v_add_u32_e32 v102, 16, v147
	v_mad_i64_i32 v[104:105], s[28:29], v102, s63, v[114:115]
	v_lshl_add_u64 v[104:105], v[104:105], 0, v[116:117]
	global_store_dwordx4 v[104:105], v[110:113], off
	s_waitcnt lgkmcnt(0)
; #define PG8_LAS __attribute__((address_space(3)))
; __device__ __forceinline__ unsigned cvt_pk_bf16(float lo, float hi) { unsigned r; asm volatile("v_cvt_pk_bf16_f32 %0, %1, %2" : "=v"(r) : "v"(lo), "v"(hi)); return r; }
;     __device__ __forceinline__ void operator()(const f32x4 (&acc)[2][2][4][2], const Unit& u, int wr, int wc, int fr, int fq, const PG8_LAS float* tab) const {
;         const int row0 = u.pm * BM + wr * 64 + fr, col0 = u.pn * HALF + wc * 32 + 8 * fq;
; #pragma unroll
;         for (int ai = 0; ai < 2; ++ai)
; #pragma unroll
;             for (int m = 0; m < 4; ++m) { const int row = row0 + ai * HALF + m * 16;
;                 const float rs = tab[ai * HALF + wr * 64 + m * 16 + fr];
;                 float hv[8];
; #pragma unroll
;                 for (int n = 0; n < 2; ++n)
; #pragma unroll
;                     for (int j = 0; j < 4; ++j) { const float g = acc[ai][0][m][n][j] * rs, up = acc[ai][1][m][n][j] * rs;
;                         const float e = __builtin_amdgcn_exp2f(g * -1.4426950408889634f);
;                         hv[4 * n + j] = g * up * __builtin_amdgcn_rcpf(1.0f + e); }
;                 u32x4 w; w.x = cvt_pk_bf16(hv[0], hv[1]); w.y = cvt_pk_bf16(hv[2], hv[3]); w.z = cvt_pk_bf16(hv[4], hv[5]); w.w = cvt_pk_bf16(hv[6], hv[7]);
;                 *(u32x4*)(H + (size_t)row * ldh + col0) = w; }
;     }
	v_mul_f32_e32 v92, v150, v92
	v_mul_f32_e32 v93, v150, v93
	v_mul_f32_e32 v94, v150, v94
	v_mul_f32_e32 v95, v150, v95
	v_mul_f32_e32 v84, v150, v84
	v_mul_f32_e32 v85, v150, v85
	v_mul_f32_e32 v86, v150, v86
	v_mul_f32_e32 v87, v150, v87
	v_mul_f32_e32 v88, v150, v88
	v_mul_f32_e32 v89, v150, v89
	v_mul_f32_e32 v90, v150, v90
	v_mul_f32_e32 v91, v150, v91
	v_mul_f32_e32 v80, v150, v80
	v_mul_f32_e32 v81, v150, v81
	v_mul_f32_e32 v82, v150, v82
	v_mul_f32_e32 v83, v150, v83
	ds_read_b32 v152, v148 offset:192
	v_mul_f32_e32 v88, v92, v88
	v_mul_f32_e32 v89, v93, v89
	v_mul_f32_e32 v90, v94, v90
	v_mul_f32_e32 v91, v95, v91
	v_mul_f32_e32 v80, v84, v80
	v_mul_f32_e32 v81, v85, v81
	v_mul_f32_e32 v82, v86, v82
	v_mul_f32_e32 v83, v87, v83
	v_mul_f32_e32 v92, 0xbfb8aa3b, v92
	v_mul_f32_e32 v93, 0xbfb8aa3b, v93
	v_mul_f32_e32 v94, 0xbfb8aa3b, v94
	v_mul_f32_e32 v95, 0xbfb8aa3b, v95
	v_mul_f32_e32 v84, 0xbfb8aa3b, v84
	v_mul_f32_e32 v85, 0xbfb8aa3b, v85
	v_mul_f32_e32 v86, 0xbfb8aa3b, v86
	v_mul_f32_e32 v87, 0xbfb8aa3b, v87
	v_exp_f32_e32 v92, v92
	v_exp_f32_e32 v93, v93
	v_exp_f32_e32 v94, v94
	v_exp_f32_e32 v95, v95
	v_exp_f32_e32 v84, v84
	v_exp_f32_e32 v85, v85
	v_exp_f32_e32 v86, v86
	v_exp_f32_e32 v87, v87
	v_add_f32_e32 v92, 1.0, v92
	v_add_f32_e32 v93, 1.0, v93
	v_add_f32_e32 v94, 1.0, v94
	v_add_f32_e32 v95, 1.0, v95
	v_add_f32_e32 v84, 1.0, v84
	v_add_f32_e32 v85, 1.0, v85
	v_add_f32_e32 v86, 1.0, v86
	v_add_f32_e32 v87, 1.0, v87
	v_rcp_f32_e32 v92, v92
	v_rcp_f32_e32 v93, v93
	v_rcp_f32_e32 v94, v94
	v_rcp_f32_e32 v95, v95
	v_rcp_f32_e32 v84, v84
	v_rcp_f32_e32 v85, v85
	v_rcp_f32_e32 v86, v86
	v_rcp_f32_e32 v87, v87
	v_mul_f32_e32 v88, v88, v92
	v_mul_f32_e32 v89, v89, v93
	v_mul_f32_e32 v90, v90, v94
	v_mul_f32_e32 v91, v91, v95
	v_mul_f32_e32 v80, v80, v84
	v_mul_f32_e32 v81, v81, v85
	v_mul_f32_e32 v82, v82, v86
	v_mul_f32_e32 v83, v83, v87
	v_cvt_pk_bf16_f32 v92, v88, v89
	v_cvt_pk_bf16_f32 v93, v90, v91
	v_cvt_pk_bf16_f32 v94, v80, v81
	v_cvt_pk_bf16_f32 v95, v82, v83
	v_add_u32_e32 v84, 32, v147
	v_mad_i64_i32 v[86:87], s[28:29], v84, s63, v[114:115]
	v_lshl_add_u64 v[86:87], v[86:87], 0, v[116:117]
	global_store_dwordx4 v[86:87], v[92:95], off
	s_waitcnt lgkmcnt(0)
	v_mul_f32_e32 v76, v152, v76
	v_mul_f32_e32 v77, v152, v77
	v_mul_f32_e32 v78, v152, v78
	v_mul_f32_e32 v79, v152, v79
	v_mul_f32_e32 v68, v152, v68
	v_mul_f32_e32 v69, v152, v69
	v_mul_f32_e32 v70, v152, v70
	v_mul_f32_e32 v71, v152, v71
	v_mul_f32_e32 v72, v152, v72
	v_mul_f32_e32 v73, v152, v73
	v_mul_f32_e32 v74, v152, v74
	v_mul_f32_e32 v75, v152, v75
	v_mul_f32_e32 v64, v152, v64
	v_mul_f32_e32 v65, v152, v65
	v_mul_f32_e32 v66, v152, v66
	v_mul_f32_e32 v67, v152, v67
	ds_read_b32 v150, v148 offset:512
	v_mul_f32_e32 v72, v76, v72
	v_mul_f32_e32 v73, v77, v73
	v_mul_f32_e32 v74, v78, v74
	v_mul_f32_e32 v75, v79, v75
	v_mul_f32_e32 v64, v68, v64
	v_mul_f32_e32 v65, v69, v65
	v_mul_f32_e32 v66, v70, v66
	v_mul_f32_e32 v67, v71, v67
	v_mul_f32_e32 v76, 0xbfb8aa3b, v76
	v_mul_f32_e32 v77, 0xbfb8aa3b, v77
	v_mul_f32_e32 v78, 0xbfb8aa3b, v78
	v_mul_f32_e32 v79, 0xbfb8aa3b, v79
	v_mul_f32_e32 v68, 0xbfb8aa3b, v68
	v_mul_f32_e32 v69, 0xbfb8aa3b, v69
	v_mul_f32_e32 v70, 0xbfb8aa3b, v70
	v_mul_f32_e32 v71, 0xbfb8aa3b, v71
	v_exp_f32_e32 v76, v76
	v_exp_f32_e32 v77, v77
	v_exp_f32_e32 v78, v78
	v_exp_f32_e32 v79, v79
	v_exp_f32_e32 v68, v68
	v_exp_f32_e32 v69, v69
	v_exp_f32_e32 v70, v70
	v_exp_f32_e32 v71, v71
	v_add_f32_e32 v76, 1.0, v76
	v_add_f32_e32 v77, 1.0, v77
	v_add_f32_e32 v78, 1.0, v78
	v_add_f32_e32 v79, 1.0, v79
	v_add_f32_e32 v68, 1.0, v68
	v_add_f32_e32 v69, 1.0, v69
	v_add_f32_e32 v70, 1.0, v70
	v_add_f32_e32 v71, 1.0, v71
	v_rcp_f32_e32 v76, v76
	v_rcp_f32_e32 v77, v77
	v_rcp_f32_e32 v78, v78
	v_rcp_f32_e32 v79, v79
	v_rcp_f32_e32 v68, v68
	v_rcp_f32_e32 v69, v69
	v_rcp_f32_e32 v70, v70
	v_rcp_f32_e32 v71, v71
	v_mul_f32_e32 v72, v72, v76
	v_mul_f32_e32 v73, v73, v77
	v_mul_f32_e32 v74, v74, v78
	v_mul_f32_e32 v75, v75, v79
	v_mul_f32_e32 v64, v64, v68
	v_mul_f32_e32 v65, v65, v69
	v_mul_f32_e32 v66, v66, v70
	v_mul_f32_e32 v67, v67, v71
	v_cvt_pk_bf16_f32 v76, v72, v73
	v_cvt_pk_bf16_f32 v77, v74, v75
	v_cvt_pk_bf16_f32 v78, v64, v65
	v_cvt_pk_bf16_f32 v79, v66, v67
	v_add_u32_e32 v68, 48, v147
	v_mad_i64_i32 v[70:71], s[28:29], v68, s63, v[114:115]
	v_lshl_add_u64 v[70:71], v[70:71], 0, v[116:117]
	global_store_dwordx4 v[70:71], v[76:79], off
	s_waitcnt lgkmcnt(0)
	v_mul_f32_e32 v60, v150, v60
	v_mul_f32_e32 v61, v150, v61
	v_mul_f32_e32 v62, v150, v62
	v_mul_f32_e32 v63, v150, v63
	v_mul_f32_e32 v52, v150, v52
	v_mul_f32_e32 v53, v150, v53
	v_mul_f32_e32 v54, v150, v54
	v_mul_f32_e32 v55, v150, v55
	v_mul_f32_e32 v56, v150, v56
	v_mul_f32_e32 v57, v150, v57
	v_mul_f32_e32 v58, v150, v58
	v_mul_f32_e32 v59, v150, v59
	v_mul_f32_e32 v48, v150, v48
	v_mul_f32_e32 v49, v150, v49
	v_mul_f32_e32 v50, v150, v50
	v_mul_f32_e32 v51, v150, v51
	ds_read_b32 v152, v148 offset:576
	v_mul_f32_e32 v56, v60, v56
	v_mul_f32_e32 v57, v61, v57
	v_mul_f32_e32 v58, v62, v58
	v_mul_f32_e32 v59, v63, v59
	v_mul_f32_e32 v48, v52, v48
	v_mul_f32_e32 v49, v53, v49
	v_mul_f32_e32 v50, v54, v50
	v_mul_f32_e32 v51, v55, v51
	v_mul_f32_e32 v60, 0xbfb8aa3b, v60
	v_mul_f32_e32 v61, 0xbfb8aa3b, v61
	v_mul_f32_e32 v62, 0xbfb8aa3b, v62
	v_mul_f32_e32 v63, 0xbfb8aa3b, v63
	v_mul_f32_e32 v52, 0xbfb8aa3b, v52
	v_mul_f32_e32 v53, 0xbfb8aa3b, v53
	v_mul_f32_e32 v54, 0xbfb8aa3b, v54
	v_mul_f32_e32 v55, 0xbfb8aa3b, v55
	v_exp_f32_e32 v60, v60
	v_exp_f32_e32 v61, v61
	v_exp_f32_e32 v62, v62
	v_exp_f32_e32 v63, v63
	v_exp_f32_e32 v52, v52
	v_exp_f32_e32 v53, v53
	v_exp_f32_e32 v54, v54
	v_exp_f32_e32 v55, v55
	v_add_f32_e32 v60, 1.0, v60
	v_add_f32_e32 v61, 1.0, v61
	v_add_f32_e32 v62, 1.0, v62
	v_add_f32_e32 v63, 1.0, v63
	v_add_f32_e32 v52, 1.0, v52
	v_add_f32_e32 v53, 1.0, v53
	v_add_f32_e32 v54, 1.0, v54
	v_add_f32_e32 v55, 1.0, v55
	v_rcp_f32_e32 v60, v60
	v_rcp_f32_e32 v61, v61
	v_rcp_f32_e32 v62, v62
	v_rcp_f32_e32 v63, v63
	v_rcp_f32_e32 v52, v52
	v_rcp_f32_e32 v53, v53
	v_rcp_f32_e32 v54, v54
	v_rcp_f32_e32 v55, v55
	v_mul_f32_e32 v56, v56, v60
	v_mul_f32_e32 v57, v57, v61
	v_mul_f32_e32 v58, v58, v62
	v_mul_f32_e32 v59, v59, v63
	v_mul_f32_e32 v48, v48, v52
	v_mul_f32_e32 v49, v49, v53
	v_mul_f32_e32 v50, v50, v54
	v_mul_f32_e32 v51, v51, v55
	v_cvt_pk_bf16_f32 v60, v56, v57
	v_cvt_pk_bf16_f32 v61, v58, v59
	v_cvt_pk_bf16_f32 v62, v48, v49
	v_cvt_pk_bf16_f32 v63, v50, v51
	v_add_u32_e32 v52, 128, v147
	v_mad_i64_i32 v[54:55], s[28:29], v52, s63, v[114:115]
	v_lshl_add_u64 v[54:55], v[54:55], 0, v[116:117]
	global_store_dwordx4 v[54:55], v[60:63], off
	s_waitcnt lgkmcnt(0)
; #define PG8_LAS __attribute__((address_space(3)))
; __device__ __forceinline__ unsigned cvt_pk_bf16(float lo, float hi) { unsigned r; asm volatile("v_cvt_pk_bf16_f32 %0, %1, %2" : "=v"(r) : "v"(lo), "v"(hi)); return r; }
;     __device__ __forceinline__ void operator()(const f32x4 (&acc)[2][2][4][2], const Unit& u, int wr, int wc, int fr, int fq, const PG8_LAS float* tab) const {
;         const int row0 = u.pm * BM + wr * 64 + fr, col0 = u.pn * HALF + wc * 32 + 8 * fq;
; #pragma unroll
;         for (int ai = 0; ai < 2; ++ai)
; #pragma unroll
;             for (int m = 0; m < 4; ++m) { const int row = row0 + ai * HALF + m * 16;
;                 const float rs = tab[ai * HALF + wr * 64 + m * 16 + fr];
;                 float hv[8];
; #pragma unroll
;                 for (int n = 0; n < 2; ++n)
; #pragma unroll
;                     for (int j = 0; j < 4; ++j) { const float g = acc[ai][0][m][n][j] * rs, up = acc[ai][1][m][n][j] * rs;
;                         const float e = __builtin_amdgcn_exp2f(g * -1.4426950408889634f);
;                         hv[4 * n + j] = g * up * __builtin_amdgcn_rcpf(1.0f + e); }
;                 u32x4 w; w.x = cvt_pk_bf16(hv[0], hv[1]); w.y = cvt_pk_bf16(hv[2], hv[3]); w.z = cvt_pk_bf16(hv[4], hv[5]); w.w = cvt_pk_bf16(hv[6], hv[7]);
;                 *(u32x4*)(H + (size_t)row * ldh + col0) = w; }
;     }
	v_mul_f32_e32 v44, v152, v44
	v_mul_f32_e32 v45, v152, v45
	v_mul_f32_e32 v46, v152, v46
	v_mul_f32_e32 v47, v152, v47
	v_mul_f32_e32 v36, v152, v36
	v_mul_f32_e32 v37, v152, v37
	v_mul_f32_e32 v38, v152, v38
	v_mul_f32_e32 v39, v152, v39
	v_mul_f32_e32 v40, v152, v40
	v_mul_f32_e32 v41, v152, v41
	v_mul_f32_e32 v42, v152, v42
	v_mul_f32_e32 v43, v152, v43
	v_mul_f32_e32 v32, v152, v32
	v_mul_f32_e32 v33, v152, v33
	v_mul_f32_e32 v34, v152, v34
	v_mul_f32_e32 v35, v152, v35
	ds_read_b32 v150, v148 offset:640
	v_mul_f32_e32 v40, v44, v40
	v_mul_f32_e32 v41, v45, v41
	v_mul_f32_e32 v42, v46, v42
	v_mul_f32_e32 v43, v47, v43
	v_mul_f32_e32 v32, v36, v32
	v_mul_f32_e32 v33, v37, v33
	v_mul_f32_e32 v34, v38, v34
	v_mul_f32_e32 v35, v39, v35
	v_mul_f32_e32 v44, 0xbfb8aa3b, v44
	v_mul_f32_e32 v45, 0xbfb8aa3b, v45
	v_mul_f32_e32 v46, 0xbfb8aa3b, v46
	v_mul_f32_e32 v47, 0xbfb8aa3b, v47
	v_mul_f32_e32 v36, 0xbfb8aa3b, v36
	v_mul_f32_e32 v37, 0xbfb8aa3b, v37
	v_mul_f32_e32 v38, 0xbfb8aa3b, v38
	v_mul_f32_e32 v39, 0xbfb8aa3b, v39
	v_exp_f32_e32 v44, v44
	v_exp_f32_e32 v45, v45
	v_exp_f32_e32 v46, v46
	v_exp_f32_e32 v47, v47
	v_exp_f32_e32 v36, v36
	v_exp_f32_e32 v37, v37
	v_exp_f32_e32 v38, v38
	v_exp_f32_e32 v39, v39
	v_add_f32_e32 v44, 1.0, v44
	v_add_f32_e32 v45, 1.0, v45
	v_add_f32_e32 v46, 1.0, v46
	v_add_f32_e32 v47, 1.0, v47
	v_add_f32_e32 v36, 1.0, v36
	v_add_f32_e32 v37, 1.0, v37
	v_add_f32_e32 v38, 1.0, v38
	v_add_f32_e32 v39, 1.0, v39
	v_rcp_f32_e32 v44, v44
	v_rcp_f32_e32 v45, v45
	v_rcp_f32_e32 v46, v46
	v_rcp_f32_e32 v47, v47
	v_rcp_f32_e32 v36, v36
	v_rcp_f32_e32 v37, v37
	v_rcp_f32_e32 v38, v38
	v_rcp_f32_e32 v39, v39
	v_mul_f32_e32 v40, v40, v44
	v_mul_f32_e32 v41, v41, v45
	v_mul_f32_e32 v42, v42, v46
	v_mul_f32_e32 v43, v43, v47
	v_mul_f32_e32 v32, v32, v36
	v_mul_f32_e32 v33, v33, v37
	v_mul_f32_e32 v34, v34, v38
	v_mul_f32_e32 v35, v35, v39
	v_cvt_pk_bf16_f32 v44, v40, v41
	v_cvt_pk_bf16_f32 v45, v42, v43
	v_cvt_pk_bf16_f32 v46, v32, v33
	v_cvt_pk_bf16_f32 v47, v34, v35
	v_add_u32_e32 v36, 144, v147
	v_mad_i64_i32 v[38:39], s[28:29], v36, s63, v[114:115]
	v_lshl_add_u64 v[38:39], v[38:39], 0, v[116:117]
	global_store_dwordx4 v[38:39], v[44:47], off
	s_waitcnt lgkmcnt(0)
	v_mul_f32_e32 v28, v150, v28
	v_mul_f32_e32 v29, v150, v29
	v_mul_f32_e32 v30, v150, v30
	v_mul_f32_e32 v31, v150, v31
	v_mul_f32_e32 v20, v150, v20
	v_mul_f32_e32 v21, v150, v21
	v_mul_f32_e32 v22, v150, v22
	v_mul_f32_e32 v23, v150, v23
	v_mul_f32_e32 v24, v150, v24
	v_mul_f32_e32 v25, v150, v25
	v_mul_f32_e32 v26, v150, v26
	v_mul_f32_e32 v27, v150, v27
	v_mul_f32_e32 v16, v150, v16
	v_mul_f32_e32 v17, v150, v17
	v_mul_f32_e32 v18, v150, v18
	v_mul_f32_e32 v19, v150, v19
	ds_read_b32 v152, v148 offset:704
	v_mul_f32_e32 v24, v28, v24
	v_mul_f32_e32 v25, v29, v25
	v_mul_f32_e32 v26, v30, v26
	v_mul_f32_e32 v27, v31, v27
	v_mul_f32_e32 v16, v20, v16
	v_mul_f32_e32 v17, v21, v17
	v_mul_f32_e32 v18, v22, v18
	v_mul_f32_e32 v19, v23, v19
	v_mul_f32_e32 v28, 0xbfb8aa3b, v28
	v_mul_f32_e32 v29, 0xbfb8aa3b, v29
	v_mul_f32_e32 v30, 0xbfb8aa3b, v30
	v_mul_f32_e32 v31, 0xbfb8aa3b, v31
	v_mul_f32_e32 v20, 0xbfb8aa3b, v20
	v_mul_f32_e32 v21, 0xbfb8aa3b, v21
	v_mul_f32_e32 v22, 0xbfb8aa3b, v22
	v_mul_f32_e32 v23, 0xbfb8aa3b, v23
	v_exp_f32_e32 v28, v28
	v_exp_f32_e32 v29, v29
	v_exp_f32_e32 v30, v30
	v_exp_f32_e32 v31, v31
	v_exp_f32_e32 v20, v20
	v_exp_f32_e32 v21, v21
	v_exp_f32_e32 v22, v22
	v_exp_f32_e32 v23, v23
	v_add_f32_e32 v28, 1.0, v28
	v_add_f32_e32 v29, 1.0, v29
	v_add_f32_e32 v30, 1.0, v30
	v_add_f32_e32 v31, 1.0, v31
	v_add_f32_e32 v20, 1.0, v20
	v_add_f32_e32 v21, 1.0, v21
	v_add_f32_e32 v22, 1.0, v22
	v_add_f32_e32 v23, 1.0, v23
	v_rcp_f32_e32 v28, v28
	v_rcp_f32_e32 v29, v29
	v_rcp_f32_e32 v30, v30
	v_rcp_f32_e32 v31, v31
	v_rcp_f32_e32 v20, v20
	v_rcp_f32_e32 v21, v21
	v_rcp_f32_e32 v22, v22
	v_rcp_f32_e32 v23, v23
	v_mul_f32_e32 v24, v24, v28
	v_mul_f32_e32 v25, v25, v29
	v_mul_f32_e32 v26, v26, v30
	v_mul_f32_e32 v27, v27, v31
	v_mul_f32_e32 v16, v16, v20
	v_mul_f32_e32 v17, v17, v21
	v_mul_f32_e32 v18, v18, v22
	v_mul_f32_e32 v19, v19, v23
	v_cvt_pk_bf16_f32 v28, v24, v25
	v_cvt_pk_bf16_f32 v29, v26, v27
	v_cvt_pk_bf16_f32 v30, v16, v17
	v_cvt_pk_bf16_f32 v31, v18, v19
	v_add_u32_e32 v20, 160, v147
	v_mad_i64_i32 v[22:23], s[28:29], v20, s63, v[114:115]
	v_lshl_add_u64 v[22:23], v[22:23], 0, v[116:117]
	global_store_dwordx4 v[22:23], v[28:31], off
	s_waitcnt lgkmcnt(0)
	v_mul_f32_e32 v12, v152, v12
	v_mul_f32_e32 v13, v152, v13
	v_mul_f32_e32 v14, v152, v14
	v_mul_f32_e32 v15, v152, v15
	v_mul_f32_e32 v4, v152, v4
	v_mul_f32_e32 v5, v152, v5
	v_mul_f32_e32 v6, v152, v6
	v_mul_f32_e32 v7, v152, v7
	v_mul_f32_e32 v8, v152, v8
	v_mul_f32_e32 v9, v152, v9
	v_mul_f32_e32 v10, v152, v10
	v_mul_f32_e32 v11, v152, v11
	v_mul_f32_e32 v0, v152, v0
	v_mul_f32_e32 v1, v152, v1
	v_mul_f32_e32 v2, v152, v2
	v_mul_f32_e32 v3, v152, v3
	v_mul_f32_e32 v8, v12, v8
	v_mul_f32_e32 v9, v13, v9
	v_mul_f32_e32 v10, v14, v10
	v_mul_f32_e32 v11, v15, v11
	v_mul_f32_e32 v0, v4, v0
	v_mul_f32_e32 v1, v5, v1
	v_mul_f32_e32 v2, v6, v2
	v_mul_f32_e32 v3, v7, v3
	v_mul_f32_e32 v12, 0xbfb8aa3b, v12
	v_mul_f32_e32 v13, 0xbfb8aa3b, v13
	v_mul_f32_e32 v14, 0xbfb8aa3b, v14
	v_mul_f32_e32 v15, 0xbfb8aa3b, v15
	v_mul_f32_e32 v4, 0xbfb8aa3b, v4
	v_mul_f32_e32 v5, 0xbfb8aa3b, v5
	v_mul_f32_e32 v6, 0xbfb8aa3b, v6
	v_mul_f32_e32 v7, 0xbfb8aa3b, v7
	v_exp_f32_e32 v12, v12
	v_exp_f32_e32 v13, v13
	v_exp_f32_e32 v14, v14
	v_exp_f32_e32 v15, v15
	v_exp_f32_e32 v4, v4
	v_exp_f32_e32 v5, v5
	v_exp_f32_e32 v6, v6
	v_exp_f32_e32 v7, v7
	v_add_f32_e32 v12, 1.0, v12
	v_add_f32_e32 v13, 1.0, v13
	v_add_f32_e32 v14, 1.0, v14
	v_add_f32_e32 v15, 1.0, v15
	v_add_f32_e32 v4, 1.0, v4
	v_add_f32_e32 v5, 1.0, v5
	v_add_f32_e32 v6, 1.0, v6
	v_add_f32_e32 v7, 1.0, v7
	v_rcp_f32_e32 v12, v12
	v_rcp_f32_e32 v13, v13
	v_rcp_f32_e32 v14, v14
	v_rcp_f32_e32 v15, v15
	v_rcp_f32_e32 v4, v4
	v_rcp_f32_e32 v5, v5
	v_rcp_f32_e32 v6, v6
	v_rcp_f32_e32 v7, v7
	v_mul_f32_e32 v8, v8, v12
	v_mul_f32_e32 v9, v9, v13
	v_mul_f32_e32 v10, v10, v14
	v_mul_f32_e32 v11, v11, v15
	v_mul_f32_e32 v0, v0, v4
	v_mul_f32_e32 v1, v1, v5
	v_mul_f32_e32 v2, v2, v6
	v_mul_f32_e32 v3, v3, v7
	v_cvt_pk_bf16_f32 v12, v8, v9
	v_cvt_pk_bf16_f32 v13, v10, v11
	v_cvt_pk_bf16_f32 v14, v0, v1
	v_cvt_pk_bf16_f32 v15, v2, v3
	v_add_u32_e32 v4, 176, v147
	v_mad_i64_i32 v[6:7], s[28:29], v4, s63, v[114:115]
	v_lshl_add_u64 v[6:7], v[6:7], 0, v[116:117]
	s_mov_b64 s[28:29], -1
	global_store_dwordx4 v[6:7], v[12:15], off
	s_cbranch_vccnz .LBB0_216
	s_andn2_b64 vcc, exec, s[14:15]
	s_cbranch_vccnz .LBB0_215
	s_barrier
	s_branch .LBB0_215

; #define PG8_LAS __attribute__((address_space(3)))
; __device__ __forceinline__ unsigned cvt_pk_bf16(float lo, float hi) { unsigned r; asm volatile("v_cvt_pk_bf16_f32 %0, %1, %2" : "=v"(r) : "v"(lo), "v"(hi)); return r; }
;     __device__ __forceinline__ void operator()(const f32x4 (&acc)[2][2][4][2], const Unit& u, int wr, int wc, int fr, int fq, const PG8_LAS float* tab) const {
;         const int row0 = u.pm * BM + wr * 64 + fr, col0 = u.pn * HALF + wc * 32 + 8 * fq;
; #pragma unroll
;         for (int ai = 0; ai < 2; ++ai)
; #pragma unroll
;             for (int m = 0; m < 4; ++m) { const int row = row0 + ai * HALF + m * 16;
;                 const float rs = tab[ai * HALF + wr * 64 + m * 16 + fr];
;                 float hv[8];
; #pragma unroll
;                 for (int n = 0; n < 2; ++n)
; #pragma unroll
;                     for (int j = 0; j < 4; ++j) { const float g = acc[ai][0][m][n][j] * rs, up = acc[ai][1][m][n][j] * rs;
;                         const float e = __builtin_amdgcn_exp2f(g * -1.4426950408889634f);
;                         hv[4 * n + j] = g * up * __builtin_amdgcn_rcpf(1.0f + e); }
;                 u32x4 w; w.x = cvt_pk_bf16(hv[0], hv[1]); w.y = cvt_pk_bf16(hv[2], hv[3]); w.z = cvt_pk_bf16(hv[4], hv[5]); w.w = cvt_pk_bf16(hv[6], hv[7]);
;                 *(u32x4*)(H + (size_t)row * ldh + col0) = w; }
;     }
.LBB0_782:
	v_lshl_add_u32 v148, s50, 10, v144
	ds_read_b32 v150, v148
	v_lshl_add_u32 v140, s29, 7, v145
	v_lshl_add_u32 v147, s28, 8, v142
	s_andn2_b64 vcc, exec, s[0:1]
	v_ashrrev_i32_e32 v141, 31, v140
	v_readlane_b32 s58, v255, 23
	v_readlane_b32 s59, v255, 24
	s_waitcnt lgkmcnt(0)
	v_mul_f32_e32 v126, v150, v126
	v_mul_f32_e32 v127, v150, v127
	v_mul_f32_e32 v128, v150, v128
	v_mul_f32_e32 v129, v150, v129
	v_mul_f32_e32 v118, v150, v118
	v_mul_f32_e32 v119, v150, v119
	v_mul_f32_e32 v120, v150, v120
	v_mul_f32_e32 v121, v150, v121
	v_mul_f32_e32 v122, v150, v122
	v_mul_f32_e32 v123, v150, v123
	v_mul_f32_e32 v124, v150, v124
	v_mul_f32_e32 v125, v150, v125
	v_mul_f32_e32 v114, v150, v114
	v_mul_f32_e32 v115, v150, v115
	v_mul_f32_e32 v116, v150, v116
	v_mul_f32_e32 v117, v150, v117
	ds_read_b32 v152, v148 offset:64
	v_mul_f32_e32 v122, v126, v122
	v_mul_f32_e32 v123, v127, v123
	v_mul_f32_e32 v124, v128, v124
	v_mul_f32_e32 v125, v129, v125
	v_mul_f32_e32 v114, v118, v114
	v_mul_f32_e32 v115, v119, v115
	v_mul_f32_e32 v116, v120, v116
	v_mul_f32_e32 v117, v121, v117
	v_mul_f32_e32 v126, 0xbfb8aa3b, v126
	v_mul_f32_e32 v127, 0xbfb8aa3b, v127
	v_mul_f32_e32 v128, 0xbfb8aa3b, v128
	v_mul_f32_e32 v129, 0xbfb8aa3b, v129
	v_mul_f32_e32 v118, 0xbfb8aa3b, v118
	v_mul_f32_e32 v119, 0xbfb8aa3b, v119
	v_mul_f32_e32 v120, 0xbfb8aa3b, v120
	v_mul_f32_e32 v121, 0xbfb8aa3b, v121
	v_exp_f32_e32 v126, v126
	v_exp_f32_e32 v127, v127
	v_exp_f32_e32 v128, v128
	v_exp_f32_e32 v129, v129
	v_exp_f32_e32 v118, v118
	v_exp_f32_e32 v119, v119
	v_exp_f32_e32 v120, v120
	v_exp_f32_e32 v121, v121
	v_add_f32_e32 v126, 1.0, v126
	v_add_f32_e32 v127, 1.0, v127
	v_add_f32_e32 v128, 1.0, v128
	v_add_f32_e32 v129, 1.0, v129
	v_add_f32_e32 v118, 1.0, v118
	v_add_f32_e32 v119, 1.0, v119
	v_add_f32_e32 v120, 1.0, v120
	v_add_f32_e32 v121, 1.0, v121
	v_rcp_f32_e32 v126, v126
	v_rcp_f32_e32 v127, v127
	v_rcp_f32_e32 v128, v128
	v_rcp_f32_e32 v129, v129
	v_rcp_f32_e32 v118, v118
	v_rcp_f32_e32 v119, v119
	v_rcp_f32_e32 v120, v120
	v_rcp_f32_e32 v121, v121
	v_mul_f32_e32 v122, v122, v126
	v_mul_f32_e32 v123, v123, v127
	v_mul_f32_e32 v124, v124, v128
	v_mul_f32_e32 v125, v125, v129
	v_mul_f32_e32 v114, v114, v118
	v_mul_f32_e32 v115, v115, v119
	v_mul_f32_e32 v116, v116, v120
	v_mul_f32_e32 v117, v117, v121
	v_cvt_pk_bf16_f32 v126, v122, v123
	v_cvt_pk_bf16_f32 v127, v124, v125
	v_cvt_pk_bf16_f32 v128, v114, v115
	v_cvt_pk_bf16_f32 v129, v116, v117
	v_lshlrev_b64 v[116:117], 1, v[140:141]
	v_mov_b64_e32 v[114:115], s[16:17]
	v_mad_i64_i32 v[120:121], s[28:29], v147, s63, v[114:115]
	v_lshl_add_u64 v[120:121], v[120:121], 0, v[116:117]
	global_store_dwordx4 v[120:121], v[126:129], off
	s_waitcnt lgkmcnt(0)
	v_mul_f32_e32 v110, v152, v110
	v_mul_f32_e32 v111, v152, v111
	v_mul_f32_e32 v112, v152, v112
	v_mul_f32_e32 v113, v152, v113
	v_mul_f32_e32 v102, v152, v102
	v_mul_f32_e32 v103, v152, v103
	v_mul_f32_e32 v104, v152, v104
	v_mul_f32_e32 v105, v152, v105
	v_mul_f32_e32 v106, v152, v106
	v_mul_f32_e32 v107, v152, v107
	v_mul_f32_e32 v108, v152, v108
	v_mul_f32_e32 v109, v152, v109
	v_mul_f32_e32 v98, v152, v98
	v_mul_f32_e32 v99, v152, v99
	v_mul_f32_e32 v100, v152, v100
	v_mul_f32_e32 v101, v152, v101
	ds_read_b32 v150, v148 offset:128
	v_mul_f32_e32 v106, v110, v106
	v_mul_f32_e32 v107, v111, v107
	v_mul_f32_e32 v108, v112, v108
	v_mul_f32_e32 v109, v113, v109
	v_mul_f32_e32 v98, v102, v98
	v_mul_f32_e32 v99, v103, v99
	v_mul_f32_e32 v100, v104, v100
	v_mul_f32_e32 v101, v105, v101
	v_mul_f32_e32 v110, 0xbfb8aa3b, v110
	v_mul_f32_e32 v111, 0xbfb8aa3b, v111
	v_mul_f32_e32 v112, 0xbfb8aa3b, v112
	v_mul_f32_e32 v113, 0xbfb8aa3b, v113
	v_mul_f32_e32 v102, 0xbfb8aa3b, v102
	v_mul_f32_e32 v103, 0xbfb8aa3b, v103
	v_mul_f32_e32 v104, 0xbfb8aa3b, v104
	v_mul_f32_e32 v105, 0xbfb8aa3b, v105
	v_exp_f32_e32 v110, v110
	v_exp_f32_e32 v111, v111
	v_exp_f32_e32 v112, v112
	v_exp_f32_e32 v113, v113
	v_exp_f32_e32 v102, v102
	v_exp_f32_e32 v103, v103
	v_exp_f32_e32 v104, v104
	v_exp_f32_e32 v105, v105
	v_add_f32_e32 v110, 1.0, v110
	v_add_f32_e32 v111, 1.0, v111
	v_add_f32_e32 v112, 1.0, v112
	v_add_f32_e32 v113, 1.0, v113
	v_add_f32_e32 v102, 1.0, v102
	v_add_f32_e32 v103, 1.0, v103
	v_add_f32_e32 v104, 1.0, v104
	v_add_f32_e32 v105, 1.0, v105
	v_rcp_f32_e32 v110, v110
	v_rcp_f32_e32 v111, v111
	v_rcp_f32_e32 v112, v112
	v_rcp_f32_e32 v113, v113
	v_rcp_f32_e32 v102, v102
	v_rcp_f32_e32 v103, v103
	v_rcp_f32_e32 v104, v104
	v_rcp_f32_e32 v105, v105
	v_mul_f32_e32 v106, v106, v110
	v_mul_f32_e32 v107, v107, v111
	v_mul_f32_e32 v108, v108, v112
	v_mul_f32_e32 v109, v109, v113
	v_mul_f32_e32 v98, v98, v102
	v_mul_f32_e32 v99, v99, v103
	v_mul_f32_e32 v100, v100, v104
	v_mul_f32_e32 v101, v101, v105
	v_cvt_pk_bf16_f32 v110, v106, v107
	v_cvt_pk_bf16_f32 v111, v108, v109
	v_cvt_pk_bf16_f32 v112, v98, v99
	v_cvt_pk_bf16_f32 v113, v100, v101
	v_add_u32_e32 v102, 16, v147
	v_mad_i64_i32 v[104:105], s[28:29], v102, s63, v[114:115]
	v_lshl_add_u64 v[104:105], v[104:105], 0, v[116:117]
	global_store_dwordx4 v[104:105], v[110:113], off
	s_waitcnt lgkmcnt(0)
; #define PG8_LAS __attribute__((address_space(3)))
; __device__ __forceinline__ unsigned cvt_pk_bf16(float lo, float hi) { unsigned r; asm volatile("v_cvt_pk_bf16_f32 %0, %1, %2" : "=v"(r) : "v"(lo), "v"(hi)); return r; }
;     __device__ __forceinline__ void operator()(const f32x4 (&acc)[2][2][4][2], const Unit& u, int wr, int wc, int fr, int fq, const PG8_LAS float* tab) const {
;         const int row0 = u.pm * BM + wr * 64 + fr, col0 = u.pn * HALF + wc * 32 + 8 * fq;
; #pragma unroll
;         for (int ai = 0; ai < 2; ++ai)
; #pragma unroll
;             for (int m = 0; m < 4; ++m) { const int row = row0 + ai * HALF + m * 16;
;                 const float rs = tab[ai * HALF + wr * 64 + m * 16 + fr];
;                 float hv[8];
; #pragma unroll
;                 for (int n = 0; n < 2; ++n)
; #pragma unroll
;                     for (int j = 0; j < 4; ++j) { const float g = acc[ai][0][m][n][j] * rs, up = acc[ai][1][m][n][j] * rs;
;                         const float e = __builtin_amdgcn_exp2f(g * -1.4426950408889634f);
;                         hv[4 * n + j] = g * up * __builtin_amdgcn_rcpf(1.0f + e); }
;                 u32x4 w; w.x = cvt_pk_bf16(hv[0], hv[1]); w.y = cvt_pk_bf16(hv[2], hv[3]); w.z = cvt_pk_bf16(hv[4], hv[5]); w.w = cvt_pk_bf16(hv[6], hv[7]);
;                 *(u32x4*)(H + (size_t)row * ldh + col0) = w; }
;     }
	v_mul_f32_e32 v92, v150, v92
	v_mul_f32_e32 v93, v150, v93
	v_mul_f32_e32 v94, v150, v94
	v_mul_f32_e32 v95, v150, v95
	v_mul_f32_e32 v84, v150, v84
	v_mul_f32_e32 v85, v150, v85
	v_mul_f32_e32 v86, v150, v86
	v_mul_f32_e32 v87, v150, v87
	v_mul_f32_e32 v88, v150, v88
	v_mul_f32_e32 v89, v150, v89
	v_mul_f32_e32 v90, v150, v90
	v_mul_f32_e32 v91, v150, v91
	v_mul_f32_e32 v80, v150, v80
	v_mul_f32_e32 v81, v150, v81
	v_mul_f32_e32 v82, v150, v82
	v_mul_f32_e32 v83, v150, v83
	ds_read_b32 v152, v148 offset:192
	v_mul_f32_e32 v88, v92, v88
	v_mul_f32_e32 v89, v93, v89
	v_mul_f32_e32 v90, v94, v90
	v_mul_f32_e32 v91, v95, v91
	v_mul_f32_e32 v80, v84, v80
	v_mul_f32_e32 v81, v85, v81
	v_mul_f32_e32 v82, v86, v82
	v_mul_f32_e32 v83, v87, v83
	v_mul_f32_e32 v92, 0xbfb8aa3b, v92
	v_mul_f32_e32 v93, 0xbfb8aa3b, v93
	v_mul_f32_e32 v94, 0xbfb8aa3b, v94
	v_mul_f32_e32 v95, 0xbfb8aa3b, v95
	v_mul_f32_e32 v84, 0xbfb8aa3b, v84
	v_mul_f32_e32 v85, 0xbfb8aa3b, v85
	v_mul_f32_e32 v86, 0xbfb8aa3b, v86
	v_mul_f32_e32 v87, 0xbfb8aa3b, v87
	v_exp_f32_e32 v92, v92
	v_exp_f32_e32 v93, v93
	v_exp_f32_e32 v94, v94
	v_exp_f32_e32 v95, v95
	v_exp_f32_e32 v84, v84
	v_exp_f32_e32 v85, v85
	v_exp_f32_e32 v86, v86
	v_exp_f32_e32 v87, v87
	v_add_f32_e32 v92, 1.0, v92
	v_add_f32_e32 v93, 1.0, v93
	v_add_f32_e32 v94, 1.0, v94
	v_add_f32_e32 v95, 1.0, v95
	v_add_f32_e32 v84, 1.0, v84
	v_add_f32_e32 v85, 1.0, v85
	v_add_f32_e32 v86, 1.0, v86
	v_add_f32_e32 v87, 1.0, v87
	v_rcp_f32_e32 v92, v92
	v_rcp_f32_e32 v93, v93
	v_rcp_f32_e32 v94, v94
	v_rcp_f32_e32 v95, v95
	v_rcp_f32_e32 v84, v84
	v_rcp_f32_e32 v85, v85
	v_rcp_f32_e32 v86, v86
	v_rcp_f32_e32 v87, v87
	v_mul_f32_e32 v88, v88, v92
	v_mul_f32_e32 v89, v89, v93
	v_mul_f32_e32 v90, v90, v94
	v_mul_f32_e32 v91, v91, v95
	v_mul_f32_e32 v80, v80, v84
	v_mul_f32_e32 v81, v81, v85
	v_mul_f32_e32 v82, v82, v86
	v_mul_f32_e32 v83, v83, v87
	v_cvt_pk_bf16_f32 v92, v88, v89
	v_cvt_pk_bf16_f32 v93, v90, v91
	v_cvt_pk_bf16_f32 v94, v80, v81
	v_cvt_pk_bf16_f32 v95, v82, v83
	v_add_u32_e32 v84, 32, v147
	v_mad_i64_i32 v[86:87], s[28:29], v84, s63, v[114:115]
	v_lshl_add_u64 v[86:87], v[86:87], 0, v[116:117]
	global_store_dwordx4 v[86:87], v[92:95], off
	s_waitcnt lgkmcnt(0)
	v_mul_f32_e32 v76, v152, v76
	v_mul_f32_e32 v77, v152, v77
	v_mul_f32_e32 v78, v152, v78
	v_mul_f32_e32 v79, v152, v79
	v_mul_f32_e32 v68, v152, v68
	v_mul_f32_e32 v69, v152, v69
	v_mul_f32_e32 v70, v152, v70
	v_mul_f32_e32 v71, v152, v71
	v_mul_f32_e32 v72, v152, v72
	v_mul_f32_e32 v73, v152, v73
	v_mul_f32_e32 v74, v152, v74
	v_mul_f32_e32 v75, v152, v75
	v_mul_f32_e32 v64, v152, v64
	v_mul_f32_e32 v65, v152, v65
	v_mul_f32_e32 v66, v152, v66
	v_mul_f32_e32 v67, v152, v67
	ds_read_b32 v150, v148 offset:512
	v_mul_f32_e32 v72, v76, v72
	v_mul_f32_e32 v73, v77, v73
	v_mul_f32_e32 v74, v78, v74
	v_mul_f32_e32 v75, v79, v75
	v_mul_f32_e32 v64, v68, v64
	v_mul_f32_e32 v65, v69, v65
	v_mul_f32_e32 v66, v70, v66
	v_mul_f32_e32 v67, v71, v67
	v_mul_f32_e32 v76, 0xbfb8aa3b, v76
	v_mul_f32_e32 v77, 0xbfb8aa3b, v77
	v_mul_f32_e32 v78, 0xbfb8aa3b, v78
	v_mul_f32_e32 v79, 0xbfb8aa3b, v79
	v_mul_f32_e32 v68, 0xbfb8aa3b, v68
	v_mul_f32_e32 v69, 0xbfb8aa3b, v69
	v_mul_f32_e32 v70, 0xbfb8aa3b, v70
	v_mul_f32_e32 v71, 0xbfb8aa3b, v71
	v_exp_f32_e32 v76, v76
	v_exp_f32_e32 v77, v77
	v_exp_f32_e32 v78, v78
	v_exp_f32_e32 v79, v79
	v_exp_f32_e32 v68, v68
	v_exp_f32_e32 v69, v69
	v_exp_f32_e32 v70, v70
	v_exp_f32_e32 v71, v71
	v_add_f32_e32 v76, 1.0, v76
	v_add_f32_e32 v77, 1.0, v77
	v_add_f32_e32 v78, 1.0, v78
	v_add_f32_e32 v79, 1.0, v79
	v_add_f32_e32 v68, 1.0, v68
	v_add_f32_e32 v69, 1.0, v69
	v_add_f32_e32 v70, 1.0, v70
	v_add_f32_e32 v71, 1.0, v71
	v_rcp_f32_e32 v76, v76
	v_rcp_f32_e32 v77, v77
	v_rcp_f32_e32 v78, v78
	v_rcp_f32_e32 v79, v79
	v_rcp_f32_e32 v68, v68
	v_rcp_f32_e32 v69, v69
	v_rcp_f32_e32 v70, v70
	v_rcp_f32_e32 v71, v71
	v_mul_f32_e32 v72, v72, v76
	v_mul_f32_e32 v73, v73, v77
	v_mul_f32_e32 v74, v74, v78
	v_mul_f32_e32 v75, v75, v79
	v_mul_f32_e32 v64, v64, v68
	v_mul_f32_e32 v65, v65, v69
	v_mul_f32_e32 v66, v66, v70
	v_mul_f32_e32 v67, v67, v71
	v_cvt_pk_bf16_f32 v76, v72, v73
	v_cvt_pk_bf16_f32 v77, v74, v75
	v_cvt_pk_bf16_f32 v78, v64, v65
	v_cvt_pk_bf16_f32 v79, v66, v67
	v_add_u32_e32 v68, 48, v147
	v_mad_i64_i32 v[70:71], s[28:29], v68, s63, v[114:115]
	v_lshl_add_u64 v[70:71], v[70:71], 0, v[116:117]
	global_store_dwordx4 v[70:71], v[76:79], off
	s_waitcnt lgkmcnt(0)
	v_mul_f32_e32 v60, v150, v60
	v_mul_f32_e32 v61, v150, v61
	v_mul_f32_e32 v62, v150, v62
	v_mul_f32_e32 v63, v150, v63
	v_mul_f32_e32 v52, v150, v52
	v_mul_f32_e32 v53, v150, v53
	v_mul_f32_e32 v54, v150, v54
	v_mul_f32_e32 v55, v150, v55
	v_mul_f32_e32 v56, v150, v56
	v_mul_f32_e32 v57, v150, v57
	v_mul_f32_e32 v58, v150, v58
	v_mul_f32_e32 v59, v150, v59
	v_mul_f32_e32 v48, v150, v48
	v_mul_f32_e32 v49, v150, v49
	v_mul_f32_e32 v50, v150, v50
	v_mul_f32_e32 v51, v150, v51
	ds_read_b32 v152, v148 offset:576
	v_mul_f32_e32 v56, v60, v56
	v_mul_f32_e32 v57, v61, v57
	v_mul_f32_e32 v58, v62, v58
	v_mul_f32_e32 v59, v63, v59
	v_mul_f32_e32 v48, v52, v48
	v_mul_f32_e32 v49, v53, v49
	v_mul_f32_e32 v50, v54, v50
	v_mul_f32_e32 v51, v55, v51
	v_mul_f32_e32 v60, 0xbfb8aa3b, v60
	v_mul_f32_e32 v61, 0xbfb8aa3b, v61
	v_mul_f32_e32 v62, 0xbfb8aa3b, v62
	v_mul_f32_e32 v63, 0xbfb8aa3b, v63
	v_mul_f32_e32 v52, 0xbfb8aa3b, v52
	v_mul_f32_e32 v53, 0xbfb8aa3b, v53
	v_mul_f32_e32 v54, 0xbfb8aa3b, v54
	v_mul_f32_e32 v55, 0xbfb8aa3b, v55
	v_exp_f32_e32 v60, v60
	v_exp_f32_e32 v61, v61
	v_exp_f32_e32 v62, v62
	v_exp_f32_e32 v63, v63
	v_exp_f32_e32 v52, v52
	v_exp_f32_e32 v53, v53
	v_exp_f32_e32 v54, v54
	v_exp_f32_e32 v55, v55
	v_add_f32_e32 v60, 1.0, v60
	v_add_f32_e32 v61, 1.0, v61
	v_add_f32_e32 v62, 1.0, v62
	v_add_f32_e32 v63, 1.0, v63
	v_add_f32_e32 v52, 1.0, v52
	v_add_f32_e32 v53, 1.0, v53
	v_add_f32_e32 v54, 1.0, v54
	v_add_f32_e32 v55, 1.0, v55
	v_rcp_f32_e32 v60, v60
	v_rcp_f32_e32 v61, v61
	v_rcp_f32_e32 v62, v62
	v_rcp_f32_e32 v63, v63
	v_rcp_f32_e32 v52, v52
	v_rcp_f32_e32 v53, v53
	v_rcp_f32_e32 v54, v54
	v_rcp_f32_e32 v55, v55
	v_mul_f32_e32 v56, v56, v60
	v_mul_f32_e32 v57, v57, v61
	v_mul_f32_e32 v58, v58, v62
	v_mul_f32_e32 v59, v59, v63
	v_mul_f32_e32 v48, v48, v52
	v_mul_f32_e32 v49, v49, v53
	v_mul_f32_e32 v50, v50, v54
	v_mul_f32_e32 v51, v51, v55
	v_cvt_pk_bf16_f32 v60, v56, v57
	v_cvt_pk_bf16_f32 v61, v58, v59
	v_cvt_pk_bf16_f32 v62, v48, v49
	v_cvt_pk_bf16_f32 v63, v50, v51
	v_add_u32_e32 v52, 128, v147
	v_mad_i64_i32 v[54:55], s[28:29], v52, s63, v[114:115]
	v_lshl_add_u64 v[54:55], v[54:55], 0, v[116:117]
	global_store_dwordx4 v[54:55], v[60:63], off
	s_waitcnt lgkmcnt(0)
; #define PG8_LAS __attribute__((address_space(3)))
; __device__ __forceinline__ unsigned cvt_pk_bf16(float lo, float hi) { unsigned r; asm volatile("v_cvt_pk_bf16_f32 %0, %1, %2" : "=v"(r) : "v"(lo), "v"(hi)); return r; }
;     __device__ __forceinline__ void operator()(const f32x4 (&acc)[2][2][4][2], const Unit& u, int wr, int wc, int fr, int fq, const PG8_LAS float* tab) const {
;         const int row0 = u.pm * BM + wr * 64 + fr, col0 = u.pn * HALF + wc * 32 + 8 * fq;
; #pragma unroll
;         for (int ai = 0; ai < 2; ++ai)
; #pragma unroll
;             for (int m = 0; m < 4; ++m) { const int row = row0 + ai * HALF + m * 16;
;                 const float rs = tab[ai * HALF + wr * 64 + m * 16 + fr];
;                 float hv[8];
; #pragma unroll
;                 for (int n = 0; n < 2; ++n)
; #pragma unroll
;                     for (int j = 0; j < 4; ++j) { const float g = acc[ai][0][m][n][j] * rs, up = acc[ai][1][m][n][j] * rs;
;                         const float e = __builtin_amdgcn_exp2f(g * -1.4426950408889634f);
;                         hv[4 * n + j] = g * up * __builtin_amdgcn_rcpf(1.0f + e); }
;                 u32x4 w; w.x = cvt_pk_bf16(hv[0], hv[1]); w.y = cvt_pk_bf16(hv[2], hv[3]); w.z = cvt_pk_bf16(hv[4], hv[5]); w.w = cvt_pk_bf16(hv[6], hv[7]);
;                 *(u32x4*)(H + (size_t)row * ldh + col0) = w; }
;     }
	v_mul_f32_e32 v44, v152, v44
	v_mul_f32_e32 v45, v152, v45
	v_mul_f32_e32 v46, v152, v46
	v_mul_f32_e32 v47, v152, v47
	v_mul_f32_e32 v36, v152, v36
	v_mul_f32_e32 v37, v152, v37
	v_mul_f32_e32 v38, v152, v38
	v_mul_f32_e32 v39, v152, v39
	v_mul_f32_e32 v40, v152, v40
	v_mul_f32_e32 v41, v152, v41
	v_mul_f32_e32 v42, v152, v42
	v_mul_f32_e32 v43, v152, v43
	v_mul_f32_e32 v32, v152, v32
	v_mul_f32_e32 v33, v152, v33
	v_mul_f32_e32 v34, v152, v34
	v_mul_f32_e32 v35, v152, v35
	ds_read_b32 v150, v148 offset:640
	v_mul_f32_e32 v40, v44, v40
	v_mul_f32_e32 v41, v45, v41
	v_mul_f32_e32 v42, v46, v42
	v_mul_f32_e32 v43, v47, v43
	v_mul_f32_e32 v32, v36, v32
	v_mul_f32_e32 v33, v37, v33
	v_mul_f32_e32 v34, v38, v34
	v_mul_f32_e32 v35, v39, v35
	v_mul_f32_e32 v44, 0xbfb8aa3b, v44
	v_mul_f32_e32 v45, 0xbfb8aa3b, v45
	v_mul_f32_e32 v46, 0xbfb8aa3b, v46
	v_mul_f32_e32 v47, 0xbfb8aa3b, v47
	v_mul_f32_e32 v36, 0xbfb8aa3b, v36
	v_mul_f32_e32 v37, 0xbfb8aa3b, v37
	v_mul_f32_e32 v38, 0xbfb8aa3b, v38
	v_mul_f32_e32 v39, 0xbfb8aa3b, v39
	v_exp_f32_e32 v44, v44
	v_exp_f32_e32 v45, v45
	v_exp_f32_e32 v46, v46
	v_exp_f32_e32 v47, v47
	v_exp_f32_e32 v36, v36
	v_exp_f32_e32 v37, v37
	v_exp_f32_e32 v38, v38
	v_exp_f32_e32 v39, v39
	v_add_f32_e32 v44, 1.0, v44
	v_add_f32_e32 v45, 1.0, v45
	v_add_f32_e32 v46, 1.0, v46
	v_add_f32_e32 v47, 1.0, v47
	v_add_f32_e32 v36, 1.0, v36
	v_add_f32_e32 v37, 1.0, v37
	v_add_f32_e32 v38, 1.0, v38
	v_add_f32_e32 v39, 1.0, v39
	v_rcp_f32_e32 v44, v44
	v_rcp_f32_e32 v45, v45
	v_rcp_f32_e32 v46, v46
	v_rcp_f32_e32 v47, v47
	v_rcp_f32_e32 v36, v36
	v_rcp_f32_e32 v37, v37
	v_rcp_f32_e32 v38, v38
	v_rcp_f32_e32 v39, v39
	v_mul_f32_e32 v40, v40, v44
	v_mul_f32_e32 v41, v41, v45
	v_mul_f32_e32 v42, v42, v46
	v_mul_f32_e32 v43, v43, v47
	v_mul_f32_e32 v32, v32, v36
	v_mul_f32_e32 v33, v33, v37
	v_mul_f32_e32 v34, v34, v38
	v_mul_f32_e32 v35, v35, v39
	v_cvt_pk_bf16_f32 v44, v40, v41
	v_cvt_pk_bf16_f32 v45, v42, v43
	v_cvt_pk_bf16_f32 v46, v32, v33
	v_cvt_pk_bf16_f32 v47, v34, v35
	v_add_u32_e32 v36, 144, v147
	v_mad_i64_i32 v[38:39], s[28:29], v36, s63, v[114:115]
	v_lshl_add_u64 v[38:39], v[38:39], 0, v[116:117]
	global_store_dwordx4 v[38:39], v[44:47], off
	s_waitcnt lgkmcnt(0)
	v_mul_f32_e32 v28, v150, v28
	v_mul_f32_e32 v29, v150, v29
	v_mul_f32_e32 v30, v150, v30
	v_mul_f32_e32 v31, v150, v31
	v_mul_f32_e32 v20, v150, v20
	v_mul_f32_e32 v21, v150, v21
	v_mul_f32_e32 v22, v150, v22
	v_mul_f32_e32 v23, v150, v23
	v_mul_f32_e32 v24, v150, v24
	v_mul_f32_e32 v25, v150, v25
	v_mul_f32_e32 v26, v150, v26
	v_mul_f32_e32 v27, v150, v27
	v_mul_f32_e32 v16, v150, v16
	v_mul_f32_e32 v17, v150, v17
	v_mul_f32_e32 v18, v150, v18
	v_mul_f32_e32 v19, v150, v19
	ds_read_b32 v152, v148 offset:704
	v_mul_f32_e32 v24, v28, v24
	v_mul_f32_e32 v25, v29, v25
	v_mul_f32_e32 v26, v30, v26
	v_mul_f32_e32 v27, v31, v27
	v_mul_f32_e32 v16, v20, v16
	v_mul_f32_e32 v17, v21, v17
	v_mul_f32_e32 v18, v22, v18
	v_mul_f32_e32 v19, v23, v19
	v_mul_f32_e32 v28, 0xbfb8aa3b, v28
	v_mul_f32_e32 v29, 0xbfb8aa3b, v29
	v_mul_f32_e32 v30, 0xbfb8aa3b, v30
	v_mul_f32_e32 v31, 0xbfb8aa3b, v31
	v_mul_f32_e32 v20, 0xbfb8aa3b, v20
	v_mul_f32_e32 v21, 0xbfb8aa3b, v21
	v_mul_f32_e32 v22, 0xbfb8aa3b, v22
	v_mul_f32_e32 v23, 0xbfb8aa3b, v23
	v_exp_f32_e32 v28, v28
	v_exp_f32_e32 v29, v29
	v_exp_f32_e32 v30, v30
	v_exp_f32_e32 v31, v31
	v_exp_f32_e32 v20, v20
	v_exp_f32_e32 v21, v21
	v_exp_f32_e32 v22, v22
	v_exp_f32_e32 v23, v23
	v_add_f32_e32 v28, 1.0, v28
	v_add_f32_e32 v29, 1.0, v29
	v_add_f32_e32 v30, 1.0, v30
	v_add_f32_e32 v31, 1.0, v31
	v_add_f32_e32 v20, 1.0, v20
	v_add_f32_e32 v21, 1.0, v21
	v_add_f32_e32 v22, 1.0, v22
	v_add_f32_e32 v23, 1.0, v23
	v_rcp_f32_e32 v28, v28
	v_rcp_f32_e32 v29, v29
	v_rcp_f32_e32 v30, v30
	v_rcp_f32_e32 v31, v31
	v_rcp_f32_e32 v20, v20
	v_rcp_f32_e32 v21, v21
	v_rcp_f32_e32 v22, v22
	v_rcp_f32_e32 v23, v23
	v_mul_f32_e32 v24, v24, v28
	v_mul_f32_e32 v25, v25, v29
	v_mul_f32_e32 v26, v26, v30
	v_mul_f32_e32 v27, v27, v31
	v_mul_f32_e32 v16, v16, v20
	v_mul_f32_e32 v17, v17, v21
	v_mul_f32_e32 v18, v18, v22
	v_mul_f32_e32 v19, v19, v23
	v_cvt_pk_bf16_f32 v28, v24, v25
	v_cvt_pk_bf16_f32 v29, v26, v27
	v_cvt_pk_bf16_f32 v30, v16, v17
	v_cvt_pk_bf16_f32 v31, v18, v19
	v_add_u32_e32 v20, 160, v147
	v_mad_i64_i32 v[22:23], s[28:29], v20, s63, v[114:115]
	v_lshl_add_u64 v[22:23], v[22:23], 0, v[116:117]
	global_store_dwordx4 v[22:23], v[28:31], off
	s_waitcnt lgkmcnt(0)
	v_mul_f32_e32 v12, v152, v12
	v_mul_f32_e32 v13, v152, v13
	v_mul_f32_e32 v14, v152, v14
	v_mul_f32_e32 v15, v152, v15
	v_mul_f32_e32 v4, v152, v4
	v_mul_f32_e32 v5, v152, v5
	v_mul_f32_e32 v6, v152, v6
	v_mul_f32_e32 v7, v152, v7
	v_mul_f32_e32 v8, v152, v8
	v_mul_f32_e32 v9, v152, v9
	v_mul_f32_e32 v10, v152, v10
	v_mul_f32_e32 v11, v152, v11
	v_mul_f32_e32 v0, v152, v0
	v_mul_f32_e32 v1, v152, v1
	v_mul_f32_e32 v2, v152, v2
	v_mul_f32_e32 v3, v152, v3
	v_mul_f32_e32 v8, v12, v8
	v_mul_f32_e32 v9, v13, v9
	v_mul_f32_e32 v10, v14, v10
	v_mul_f32_e32 v11, v15, v11
	v_mul_f32_e32 v0, v4, v0
	v_mul_f32_e32 v1, v5, v1
	v_mul_f32_e32 v2, v6, v2
	v_mul_f32_e32 v3, v7, v3
	v_mul_f32_e32 v12, 0xbfb8aa3b, v12
	v_mul_f32_e32 v13, 0xbfb8aa3b, v13
	v_mul_f32_e32 v14, 0xbfb8aa3b, v14
	v_mul_f32_e32 v15, 0xbfb8aa3b, v15
	v_mul_f32_e32 v4, 0xbfb8aa3b, v4
	v_mul_f32_e32 v5, 0xbfb8aa3b, v5
	v_mul_f32_e32 v6, 0xbfb8aa3b, v6
	v_mul_f32_e32 v7, 0xbfb8aa3b, v7
	v_exp_f32_e32 v12, v12
	v_exp_f32_e32 v13, v13
	v_exp_f32_e32 v14, v14
	v_exp_f32_e32 v15, v15
	v_exp_f32_e32 v4, v4
	v_exp_f32_e32 v5, v5
	v_exp_f32_e32 v6, v6
	v_exp_f32_e32 v7, v7
	v_add_f32_e32 v12, 1.0, v12
	v_add_f32_e32 v13, 1.0, v13
	v_add_f32_e32 v14, 1.0, v14
	v_add_f32_e32 v15, 1.0, v15
	v_add_f32_e32 v4, 1.0, v4
	v_add_f32_e32 v5, 1.0, v5
	v_add_f32_e32 v6, 1.0, v6
	v_add_f32_e32 v7, 1.0, v7
	v_rcp_f32_e32 v12, v12
	v_rcp_f32_e32 v13, v13
	v_rcp_f32_e32 v14, v14
	v_rcp_f32_e32 v15, v15
	v_rcp_f32_e32 v4, v4
	v_rcp_f32_e32 v5, v5
	v_rcp_f32_e32 v6, v6
	v_rcp_f32_e32 v7, v7
	v_mul_f32_e32 v8, v8, v12
	v_mul_f32_e32 v9, v9, v13
	v_mul_f32_e32 v10, v10, v14
	v_mul_f32_e32 v11, v11, v15
	v_mul_f32_e32 v0, v0, v4
	v_mul_f32_e32 v1, v1, v5
	v_mul_f32_e32 v2, v2, v6
	v_mul_f32_e32 v3, v3, v7
	v_cvt_pk_bf16_f32 v12, v8, v9
	v_cvt_pk_bf16_f32 v13, v10, v11
	v_cvt_pk_bf16_f32 v14, v0, v1
	v_cvt_pk_bf16_f32 v15, v2, v3
	v_add_u32_e32 v4, 176, v147
	v_mad_i64_i32 v[6:7], s[28:29], v4, s63, v[114:115]
	v_lshl_add_u64 v[6:7], v[6:7], 0, v[116:117]
	s_mov_b64 s[28:29], -1
	global_store_dwordx4 v[6:7], v[12:15], off
	s_cbranch_vccnz .LBB0_775
	s_andn2_b64 vcc, exec, s[14:15]
	s_cbranch_vccnz .LBB0_774
	s_barrier
	s_branch .LBB0_774
